# attention: static priority 3 for the younger wave half, no per-segment toggles
# baseline (speedup 1.0000x reference)
.LatB_pre:
	s_setprio 3
